# prompt-MLA loop: s_setprio 1 around the QK and PV MFMA clusters (none before); on top of sample-MLA priority changes
# baseline (speedup 1.0000x reference)
.LBB0_1065:
	s_cmp_gt_i32 s20, s13
	s_cbranch_scc1 .LBB0_1067
	s_mul_hi_u32 s19, s20, 0xaaaaaaab
	s_lshr_b32 s47, s19, 1
	s_mul_i32 s47, s47, 0x12300
	v_subrev_u32_e32 v207, s47, v175
	v_add_u32_e32 v208, s36, v186
	v_subrev_u32_e32 v206, s47, v176
	v_add_u32_e32 v12, v208, v207
	v_add_u32_e32 v82, v208, v206
	s_setprio 1
	ds_read_b128 v[4:7], v12
	ds_read_b128 v[8:11], v82
	ds_read_b128 v[12:15], v12 offset:8192
	ds_read_b128 v[188:191], v82 offset:8192
	s_waitcnt lgkmcnt(3)
	v_mfma_f32_32x32x16_bf16 v[98:113], v[4:7], v[114:117], 0
	v_subrev_u32_e32 v205, s47, v177
	v_add_u32_e32 v82, v208, v205
	ds_read_b128 v[192:195], v82
	ds_read_b128 v[196:199], v82 offset:8192
	v_subrev_u32_e32 v204, s47, v178
	v_subrev_u32_e32 v200, s47, v179
	v_subrev_u32_e32 v163, s47, v180
	v_add_u32_e32 v163, v208, v163
	s_waitcnt lgkmcnt(3)
	v_mfma_f32_32x32x16_bf16 v[82:97], v[12:15], v[114:117], 0
	v_add_u32_e32 v12, v208, v204
	ds_read_b128 v[4:7], v12
	ds_read_b128 v[12:15], v12 offset:8192
	v_subrev_u32_e32 v17, s47, v181
	v_subrev_u32_e32 v16, s47, v182
	v_add_u32_e32 v16, v208, v16
	v_subrev_u32_e32 v2, s47, v185
	s_add_i32 s19, s36, 0
	v_mfma_f32_32x32x16_bf16 v[98:113], v[8:11], v[118:121], v[98:113]
	v_add_u32_e32 v2, s19, v2
	v_subrev_u32_e32 v1, s47, v183
	v_add_u32_e32 v1, s19, v1
	s_and_b32 s19, s50, 0xc000
	s_waitcnt lgkmcnt(4)
	v_mfma_f32_32x32x16_bf16 v[82:97], v[188:191], v[118:121], v[82:97]
	v_add_u32_e32 v188, v208, v200
	ds_read_b128 v[8:11], v188
	ds_read_b128 v[188:191], v188 offset:8192
	s_waitcnt lgkmcnt(5)
	v_mfma_f32_32x32x16_bf16 v[98:113], v[192:195], v[122:125], v[98:113]
	s_waitcnt lgkmcnt(4)
	v_mfma_f32_32x32x16_bf16 v[82:97], v[196:199], v[122:125], v[82:97]
	ds_read_b128 v[192:195], v163
	ds_read_b128 v[196:199], v163 offset:8192
	s_waitcnt lgkmcnt(5)
	v_mfma_f32_32x32x16_bf16 v[98:113], v[4:7], v[126:129], v[98:113]
	s_waitcnt lgkmcnt(4)
	v_mfma_f32_32x32x16_bf16 v[82:97], v[12:15], v[126:129], v[82:97]
	v_add_u32_e32 v12, v208, v17
	ds_read_b128 v[4:7], v12
	ds_read_b128 v[12:15], v12 offset:8192
	s_waitcnt lgkmcnt(5)
	v_mfma_f32_32x32x16_bf16 v[98:113], v[8:11], v[130:133], v[98:113]
	s_waitcnt lgkmcnt(4)
	v_mfma_f32_32x32x16_bf16 v[82:97], v[188:191], v[130:133], v[82:97]
	ds_read_b128 v[8:11], v16
	ds_read_b128 v[188:191], v16 offset:8192
	v_add_u32_e32 v16, s36, v187
	v_add_u32_e32 v17, v16, v207
	s_waitcnt lgkmcnt(5)
	v_mfma_f32_32x32x16_bf16 v[98:113], v[192:195], v[134:137], v[98:113]
	s_waitcnt lgkmcnt(4)
	v_mfma_f32_32x32x16_bf16 v[82:97], v[196:199], v[134:137], v[82:97]
	ds_read_b128 v[192:195], v17 offset:16384
	ds_read_b128 v[196:199], v17 offset:20480
	v_add_u32_e32 v17, v16, v205
	s_waitcnt lgkmcnt(5)
	v_mfma_f32_32x32x16_bf16 v[98:113], v[4:7], v[138:141], v[98:113]
	s_waitcnt lgkmcnt(4)
	v_mfma_f32_32x32x16_bf16 v[82:97], v[12:15], v[138:141], v[82:97]
	v_add_u32_e32 v12, v16, v206
	ds_read_b128 v[4:7], v12 offset:16384
	ds_read_b128 v[12:15], v12 offset:20480
	v_add_u32_e32 v16, v16, v204
	s_waitcnt lgkmcnt(5)
	v_mfma_f32_32x32x16_bf16 v[98:113], v[8:11], v[142:145], v[98:113]
	s_waitcnt lgkmcnt(4)
	v_mfma_f32_32x32x16_bf16 v[82:97], v[188:191], v[142:145], v[82:97]
	ds_read_b128 v[8:11], v17 offset:16384
	ds_read_b128 v[188:191], v17 offset:20480
	s_waitcnt lgkmcnt(5)
	v_mfma_f32_32x32x16_bf16 v[98:113], v[192:195], v[146:149], v[98:113]
	s_waitcnt lgkmcnt(4)
	v_mfma_f32_32x32x16_bf16 v[82:97], v[196:199], v[146:149], v[82:97]
	ds_read_b128 v[192:195], v16 offset:16384
	ds_read_b128 v[196:199], v16 offset:20480
	s_waitcnt lgkmcnt(5)
	v_mfma_f32_32x32x16_bf16 v[98:113], v[4:7], v[150:153], v[98:113]
	ds_read_b128 v[4:7], v2
	v_add_u32_e32 v2, s36, v184
	v_subrev_u32_e32 v2, s47, v2
	s_waitcnt lgkmcnt(5)
	v_mfma_f32_32x32x16_bf16 v[82:97], v[12:15], v[150:153], v[82:97]
	s_waitcnt lgkmcnt(4)
	v_mfma_f32_32x32x16_bf16 v[98:113], v[8:11], v[154:157], v[98:113]
	s_waitcnt lgkmcnt(3)
	v_mfma_f32_32x32x16_bf16 v[82:97], v[188:191], v[154:157], v[82:97]
	s_waitcnt lgkmcnt(2)
	v_mfma_f32_32x32x16_bf16 v[98:113], v[192:195], v[158:161], v[98:113]
	s_waitcnt lgkmcnt(1)
	v_mfma_f32_32x32x16_bf16 v[82:97], v[196:199], v[158:161], v[82:97]
	s_setprio 0
	ds_read_b128 v[8:11], v2 offset:24608
	ds_read_b128 v[12:15], v2 offset:24640
	ds_read_b128 v[188:191], v2 offset:24672
	ds_read_b128 v[192:195], v2 offset:24704
	ds_read_b128 v[196:199], v2 offset:24736
	ds_read_b128 v[204:207], v2 offset:24768
	ds_read_b128 v[214:217], v1
	s_waitcnt lgkmcnt(7)
	s_nop 1
	v_fma_f32 v1, v98, v4, -v213
	v_fma_f32 v4, v99, v5, -v213
	v_exp_f32_e32 v16, v4
	v_fma_f32 v4, v100, v6, -v213
	v_exp_f32_e32 v98, v4
	v_fma_f32 v4, v101, v7, -v213
	v_exp_f32_e32 v100, v4
	s_waitcnt lgkmcnt(6)
	v_fma_f32 v4, v102, v8, -v213
	v_exp_f32_e32 v102, v4
	v_fma_f32 v4, v103, v9, -v213
	v_exp_f32_e32 v218, v4
	v_fma_f32 v4, v104, v10, -v213
	v_exp_f32_e32 v104, v4
	v_fma_f32 v4, v105, v11, -v213
	v_exp_f32_e32 v220, v4
	s_waitcnt lgkmcnt(5)
	v_fma_f32 v4, v106, v12, -v213
	v_exp_f32_e32 v106, v4
	v_fma_f32 v4, v107, v13, -v213
	v_exp_f32_e32 v222, v4
	v_fma_f32 v4, v108, v14, -v213
	v_exp_f32_e32 v108, v4
	v_fma_f32 v4, v109, v15, -v213
	v_exp_f32_e32 v1, v1
	v_exp_f32_e32 v224, v4
	s_waitcnt lgkmcnt(4)
	v_fma_f32 v4, v110, v188, -v213
	v_exp_f32_e32 v110, v4
	v_fma_f32 v4, v111, v189, -v213
	v_exp_f32_e32 v188, v4
	v_fma_f32 v4, v112, v190, -v213
	v_exp_f32_e32 v112, v4
	v_fma_f32 v4, v113, v191, -v213
	v_add_f32_e32 v2, 0, v1
	v_exp_f32_e32 v190, v4
	v_cvt_pk_bf16_f32 v4, v1, v16
	s_waitcnt lgkmcnt(3)
	v_fma_f32 v1, v82, v192, -v213
	v_exp_f32_e32 v17, v1
	v_fma_f32 v1, v83, v193, -v213
	v_exp_f32_e32 v99, v1
	v_fma_f32 v1, v84, v194, -v213
	v_exp_f32_e32 v101, v1
	v_fma_f32 v1, v85, v195, -v213
	v_exp_f32_e32 v103, v1
	s_waitcnt lgkmcnt(2)
	v_fma_f32 v1, v86, v196, -v213
	v_pk_add_f32 v[12:13], v[16:17], v[2:3]
	v_exp_f32_e32 v219, v1
	v_fma_f32 v1, v87, v197, -v213
	v_pk_add_f32 v[12:13], v[98:99], v[12:13]
	v_exp_f32_e32 v105, v1
	v_fma_f32 v1, v88, v198, -v213
	v_pk_add_f32 v[12:13], v[100:101], v[12:13]
	v_exp_f32_e32 v221, v1
	v_fma_f32 v1, v89, v199, -v213
	v_pk_add_f32 v[12:13], v[102:103], v[12:13]
	v_exp_f32_e32 v107, v1
	s_waitcnt lgkmcnt(1)
	v_fma_f32 v1, v90, v204, -v213
	v_exp_f32_e32 v223, v1
	v_fma_f32 v1, v91, v205, -v213
	v_pk_add_f32 v[12:13], v[218:219], v[12:13]
	v_exp_f32_e32 v109, v1
	v_fma_f32 v1, v92, v206, -v213
	v_pk_add_f32 v[12:13], v[104:105], v[12:13]
	v_exp_f32_e32 v225, v1
	v_fma_f32 v1, v93, v207, -v213
	v_pk_add_f32 v[12:13], v[220:221], v[12:13]
	v_exp_f32_e32 v111, v1
	s_waitcnt lgkmcnt(0)
	v_fma_f32 v1, v94, v214, -v213
	v_pk_add_f32 v[12:13], v[106:107], v[12:13]
	v_exp_f32_e32 v189, v1
	v_fma_f32 v1, v95, v215, -v213
	v_pk_add_f32 v[12:13], v[222:223], v[12:13]
	v_exp_f32_e32 v113, v1
	v_fma_f32 v1, v96, v216, -v213
	v_pk_add_f32 v[12:13], v[108:109], v[12:13]
	v_exp_f32_e32 v191, v1
	v_fma_f32 v1, v97, v217, -v213
	v_pk_add_f32 v[12:13], v[224:225], v[12:13]
	v_exp_f32_e32 v163, v1
	v_pk_add_f32 v[12:13], v[110:111], v[12:13]
	v_cvt_pk_bf16_f32 v5, v98, v100
	v_pk_add_f32 v[12:13], v[188:189], v[12:13]
	v_cvt_pk_bf16_f32 v6, v102, v218
	v_pk_add_f32 v[12:13], v[112:113], v[12:13]
	v_cvt_pk_bf16_f32 v7, v104, v220
	v_pk_add_f32 v[12:13], v[190:191], v[12:13]
	v_cvt_pk_bf16_f32 v8, v106, v222
	v_pk_add_f32 v[12:13], v[162:163], v[12:13]
	v_cvt_pk_bf16_f32 v9, v108, v224
	v_cvt_pk_bf16_f32 v10, v110, v188
	v_cvt_pk_bf16_f32 v11, v112, v190
	v_add_f32_e32 v162, v12, v13
	v_cvt_pk_bf16_f32 v12, v17, v99
	v_cvt_pk_bf16_f32 v13, v101, v103
	v_cvt_pk_bf16_f32 v14, v219, v105
	v_cvt_pk_bf16_f32 v15, v221, v107
	v_cvt_pk_bf16_f32 v82, v223, v109
	v_cvt_pk_bf16_f32 v83, v225, v111
	v_cvt_pk_bf16_f32 v84, v189, v113
	v_cvt_pk_bf16_f32 v85, v191, v163
	v_permlane32_swap_b32_e32 v4, v6
	v_permlane32_swap_b32_e32 v5, v7
	v_permlane32_swap_b32_e32 v8, v10
	v_permlane32_swap_b32_e32 v9, v11
	v_permlane32_swap_b32_e32 v12, v14
	v_permlane32_swap_b32_e32 v13, v15
	v_permlane32_swap_b32_e32 v82, v84
	v_permlane32_swap_b32_e32 v83, v85
	v_add_u32_e32 v1, s19, v174
	s_setprio 1
	ds_read_b64_tr_b16 v[86:87], v1 offset:0
	ds_read_b64_tr_b16 v[88:89], v1 offset:2048
	ds_read_b64_tr_b16 v[90:91], v1 offset:512
	ds_read_b64_tr_b16 v[92:93], v1 offset:2560
	ds_read_b64_tr_b16 v[94:95], v1 offset:1024
	ds_read_b64_tr_b16 v[96:97], v1 offset:3072
	ds_read_b64_tr_b16 v[98:99], v1 offset:1536
	ds_read_b64_tr_b16 v[100:101], v1 offset:3584
	ds_read_b64_tr_b16 v[102:103], v1 offset:4096
	ds_read_b64_tr_b16 v[104:105], v1 offset:6144
	ds_read_b64_tr_b16 v[106:107], v1 offset:4608
	ds_read_b64_tr_b16 v[108:109], v1 offset:6656
	ds_read_b64_tr_b16 v[110:111], v1 offset:5120
	ds_read_b64_tr_b16 v[112:113], v1 offset:7168
	ds_read_b64_tr_b16 v[188:189], v1 offset:5632
	ds_read_b64_tr_b16 v[190:191], v1 offset:7680
	s_waitcnt lgkmcnt(8)
	s_nop 0
	v_mfma_f32_32x32x16_bf16 v[66:81], v[4:7], v[86:89], v[66:81]
	v_mfma_f32_32x32x16_bf16 v[50:65], v[4:7], v[90:93], v[50:65]
	v_mfma_f32_32x32x16_bf16 v[34:49], v[4:7], v[94:97], v[34:49]
	v_mfma_f32_32x32x16_bf16 v[18:33], v[4:7], v[98:101], v[18:33]
	ds_read_b64_tr_b16 v[4:5], v1 offset:8192
	ds_read_b64_tr_b16 v[6:7], v1 offset:10240
	ds_read_b64_tr_b16 v[86:87], v1 offset:8704
	ds_read_b64_tr_b16 v[88:89], v1 offset:10752
	ds_read_b64_tr_b16 v[90:91], v1 offset:9216
	ds_read_b64_tr_b16 v[92:93], v1 offset:11264
	ds_read_b64_tr_b16 v[94:95], v1 offset:9728
	ds_read_b64_tr_b16 v[96:97], v1 offset:11776
	s_waitcnt lgkmcnt(8)
	v_mfma_f32_32x32x16_bf16 v[66:81], v[8:11], v[102:105], v[66:81]
	v_mfma_f32_32x32x16_bf16 v[50:65], v[8:11], v[106:109], v[50:65]
	v_mfma_f32_32x32x16_bf16 v[34:49], v[8:11], v[110:113], v[34:49]
	v_mfma_f32_32x32x16_bf16 v[18:33], v[8:11], v[188:191], v[18:33]
	ds_read_b64_tr_b16 v[8:9], v1 offset:12288
	ds_read_b64_tr_b16 v[10:11], v1 offset:14336
	ds_read_b64_tr_b16 v[98:99], v1 offset:12800
	ds_read_b64_tr_b16 v[100:101], v1 offset:14848
	ds_read_b64_tr_b16 v[102:103], v1 offset:13312
	ds_read_b64_tr_b16 v[104:105], v1 offset:15360
	ds_read_b64_tr_b16 v[106:107], v1 offset:13824
	ds_read_b64_tr_b16 v[108:109], v1 offset:15872
	s_waitcnt lgkmcnt(8)
	v_mfma_f32_32x32x16_bf16 v[66:81], v[12:15], v[4:7], v[66:81]
	v_mfma_f32_32x32x16_bf16 v[50:65], v[12:15], v[86:89], v[50:65]
	v_mfma_f32_32x32x16_bf16 v[34:49], v[12:15], v[90:93], v[34:49]
	v_mfma_f32_32x32x16_bf16 v[18:33], v[12:15], v[94:97], v[18:33]
	s_waitcnt lgkmcnt(0)
	v_mfma_f32_32x32x16_bf16 v[66:81], v[82:85], v[8:11], v[66:81]
	v_mfma_f32_32x32x16_bf16 v[50:65], v[82:85], v[98:101], v[50:65]
	v_mfma_f32_32x32x16_bf16 v[34:49], v[82:85], v[102:105], v[34:49]
	v_mfma_f32_32x32x16_bf16 v[18:33], v[82:85], v[106:109], v[18:33]
	s_setprio 0
.LBB0_1067:
	s_addk_i32 s36, 0x6100
	s_add_u32 s50, s50, 0x4000
	s_addc_u32 s51, s51, 0
	s_add_u32 s52, s52, 0x2000
	s_addc_u32 s53, s53, 0
	s_add_u32 s48, s48, 0x100
	s_addc_u32 s49, s49, 0
	s_add_i32 s1, s1, 1
	s_cmp_eq_u32 s9, s37
	s_cbranch_scc1 .LBB0_1069
	s_mov_b32 s20, s37
	s_add_i32 s37, s20, 1
	s_cmp_ge_u32 s37, s9
	s_mov_b64 s[54:55], -1
	s_cbranch_scc1 .LBB0_1056
	s_branch .LBB0_1057
	s_nop 0
	s_nop 0
	s_nop 0
	s_nop 0
	s_nop 0
	s_nop 0
	s_nop 0
	s_nop 0
	s_nop 0
	s_nop 0
	s_nop 0
	s_nop 0
